# split-K partial tiles of the last row tile go to per-piece slabs (plain stores) and are summed in piece order by the owning wave at the next norm phase, instead of scattered float atomics; WKV derive
# speedup vs baseline: 1.2571x; 1.0722x over previous
.LBB0_2885:
	v_lshl_add_u32 v140, s73, 8, v154
	v_ashrrev_i32_e32 v141, 31, v140
	v_readlane_b32 s38, v250, 41
	v_lshl_or_b32 v142, s74, 8, v156
	v_lshlrev_b64 v[144:145], 12, v[140:141]
	v_readlane_b32 s39, v250, 42
	v_ashrrev_i32_e32 v143, 31, v142
	v_or_b32_e32 v148, 16, v140
	v_lshl_add_u64 v[152:153], s[38:39], 0, v[144:145]
	v_or_b32_e32 v146, 32, v140
	v_or_b32_e32 v144, 48, v140
	v_lshl_add_u64 v[150:151], v[142:143], 2, v[152:153]
	s_mov_b64 s[38:39], -1
	s_andn2_b64 vcc, exec, s[56:57]
	v_lshlrev_b64 v[142:143], 2, v[142:143]
	v_ashrrev_i32_e32 v149, 31, v148
	v_ashrrev_i32_e32 v147, 31, v146
	v_ashrrev_i32_e32 v145, 31, v144
	s_cbranch_vccnz .LBB0_2888
	v_mov_b32_e32 v133, v132
	s_add_i32 s38, s69, -1
	s_mul_i32 s38, s38, s96
	s_add_i32 s38, s38, s2
	s_addk_i32 s38, 0xff00
	s_lshr_b32 s38, s38, 2
	s_lshl_b32 s38, s38, 20
	s_add_u32 s38, s38, 0x1bfe0000
	s_mov_b32 s39, 0
	v_lshl_add_u64 v[208:209], v[150:151], 0, s[38:39]
	v_pk_mul_f32 v[160:161], v[134:135], v[126:127]
	v_pk_mul_f32 v[162:163], v[132:133], v[128:129]
	global_store_dwordx4 v[208:209], v[160:163], off
	v_pk_mul_f32 v[164:165], v[134:135], v[122:123]
	v_pk_mul_f32 v[166:167], v[132:133], v[124:125]
	global_store_dwordx4 v[208:209], v[164:167], off offset:64
	v_pk_mul_f32 v[168:169], v[134:135], v[118:119]
	v_pk_mul_f32 v[170:171], v[132:133], v[120:121]
	global_store_dwordx4 v[208:209], v[168:171], off offset:512
	v_pk_mul_f32 v[172:173], v[134:135], v[114:115]
	v_pk_mul_f32 v[174:175], v[132:133], v[116:117]
	global_store_dwordx4 v[208:209], v[172:175], off offset:576
	s_mov_b64 s[38:39], 0x10000
	v_lshl_add_u64 v[210:211], v[208:209], 0, s[38:39]
	v_pk_mul_f32 v[160:161], v[134:135], v[110:111]
	v_pk_mul_f32 v[162:163], v[132:133], v[112:113]
	global_store_dwordx4 v[210:211], v[160:163], off
	v_pk_mul_f32 v[164:165], v[134:135], v[106:107]
	v_pk_mul_f32 v[166:167], v[132:133], v[108:109]
	global_store_dwordx4 v[210:211], v[164:167], off offset:64
	v_pk_mul_f32 v[168:169], v[134:135], v[102:103]
	v_pk_mul_f32 v[170:171], v[132:133], v[104:105]
	global_store_dwordx4 v[210:211], v[168:171], off offset:512
	v_pk_mul_f32 v[172:173], v[134:135], v[98:99]
	v_pk_mul_f32 v[174:175], v[132:133], v[100:101]
	global_store_dwordx4 v[210:211], v[172:175], off offset:576
	s_mov_b64 s[38:39], 0x20000
	v_lshl_add_u64 v[178:179], v[208:209], 0, s[38:39]
	v_pk_mul_f32 v[160:161], v[134:135], v[94:95]
	v_pk_mul_f32 v[162:163], v[132:133], v[96:97]
	global_store_dwordx4 v[178:179], v[160:163], off
	v_pk_mul_f32 v[164:165], v[134:135], v[90:91]
	v_pk_mul_f32 v[166:167], v[132:133], v[92:93]
	global_store_dwordx4 v[178:179], v[164:167], off offset:64
	v_pk_mul_f32 v[168:169], v[134:135], v[86:87]
	v_pk_mul_f32 v[170:171], v[132:133], v[88:89]
	global_store_dwordx4 v[178:179], v[168:171], off offset:512
	v_pk_mul_f32 v[172:173], v[134:135], v[82:83]
	v_pk_mul_f32 v[174:175], v[132:133], v[84:85]
	global_store_dwordx4 v[178:179], v[172:175], off offset:576
	s_mov_b64 s[38:39], 0x30000
	v_lshl_add_u64 v[210:211], v[208:209], 0, s[38:39]
	v_pk_mul_f32 v[160:161], v[134:135], v[76:77]
	v_pk_mul_f32 v[162:163], v[132:133], v[78:79]
	global_store_dwordx4 v[210:211], v[160:163], off
	v_pk_mul_f32 v[164:165], v[134:135], v[72:73]
	v_pk_mul_f32 v[166:167], v[132:133], v[74:75]
	global_store_dwordx4 v[210:211], v[164:167], off offset:64
	v_pk_mul_f32 v[168:169], v[134:135], v[68:69]
	v_pk_mul_f32 v[170:171], v[132:133], v[70:71]
	global_store_dwordx4 v[210:211], v[168:171], off offset:512
	v_pk_mul_f32 v[172:173], v[134:135], v[64:65]
	v_pk_mul_f32 v[174:175], v[132:133], v[66:67]
	global_store_dwordx4 v[210:211], v[172:175], off offset:576
	s_mov_b64 s[38:39], 0x80000
	v_lshl_add_u64 v[178:179], v[208:209], 0, s[38:39]
	v_pk_mul_f32 v[160:161], v[134:135], v[60:61]
	v_pk_mul_f32 v[162:163], v[132:133], v[62:63]
	global_store_dwordx4 v[178:179], v[160:163], off
	v_pk_mul_f32 v[164:165], v[134:135], v[56:57]
	v_pk_mul_f32 v[166:167], v[132:133], v[58:59]
	global_store_dwordx4 v[178:179], v[164:167], off offset:64
	v_pk_mul_f32 v[168:169], v[134:135], v[52:53]
	v_pk_mul_f32 v[170:171], v[132:133], v[54:55]
	global_store_dwordx4 v[178:179], v[168:171], off offset:512
	v_pk_mul_f32 v[172:173], v[134:135], v[48:49]
	v_pk_mul_f32 v[174:175], v[132:133], v[50:51]
	global_store_dwordx4 v[178:179], v[172:175], off offset:576
	s_mov_b64 s[38:39], 0x90000
	v_lshl_add_u64 v[210:211], v[208:209], 0, s[38:39]
	v_pk_mul_f32 v[160:161], v[134:135], v[44:45]
	v_pk_mul_f32 v[162:163], v[132:133], v[46:47]
	global_store_dwordx4 v[210:211], v[160:163], off
	v_pk_mul_f32 v[164:165], v[134:135], v[40:41]
	v_pk_mul_f32 v[166:167], v[132:133], v[42:43]
	global_store_dwordx4 v[210:211], v[164:167], off offset:64
	v_pk_mul_f32 v[168:169], v[134:135], v[36:37]
	v_pk_mul_f32 v[170:171], v[132:133], v[38:39]
	global_store_dwordx4 v[210:211], v[168:171], off offset:512
	v_pk_mul_f32 v[172:173], v[134:135], v[32:33]
	v_pk_mul_f32 v[174:175], v[132:133], v[34:35]
	global_store_dwordx4 v[210:211], v[172:175], off offset:576
	s_mov_b64 s[38:39], 0xa0000
	v_lshl_add_u64 v[178:179], v[208:209], 0, s[38:39]
	v_pk_mul_f32 v[160:161], v[134:135], v[28:29]
	v_pk_mul_f32 v[162:163], v[132:133], v[30:31]
	global_store_dwordx4 v[178:179], v[160:163], off
	v_pk_mul_f32 v[164:165], v[134:135], v[24:25]
	v_pk_mul_f32 v[166:167], v[132:133], v[26:27]
	global_store_dwordx4 v[178:179], v[164:167], off offset:64
	v_pk_mul_f32 v[168:169], v[134:135], v[20:21]
	v_pk_mul_f32 v[170:171], v[132:133], v[22:23]
	global_store_dwordx4 v[178:179], v[168:171], off offset:512
	v_pk_mul_f32 v[172:173], v[134:135], v[16:17]
	v_pk_mul_f32 v[174:175], v[132:133], v[18:19]
	global_store_dwordx4 v[178:179], v[172:175], off offset:576
	s_mov_b64 s[38:39], 0xb0000
	v_lshl_add_u64 v[210:211], v[208:209], 0, s[38:39]
	v_pk_mul_f32 v[160:161], v[134:135], v[12:13]
	v_pk_mul_f32 v[162:163], v[132:133], v[14:15]
	global_store_dwordx4 v[210:211], v[160:163], off
	v_pk_mul_f32 v[164:165], v[134:135], v[8:9]
	v_pk_mul_f32 v[166:167], v[132:133], v[10:11]
	global_store_dwordx4 v[210:211], v[164:167], off offset:64
	v_pk_mul_f32 v[168:169], v[134:135], v[4:5]
	v_pk_mul_f32 v[170:171], v[132:133], v[6:7]
	global_store_dwordx4 v[210:211], v[168:171], off offset:512
	v_pk_mul_f32 v[172:173], v[134:135], v[0:1]
	v_pk_mul_f32 v[174:175], v[132:133], v[2:3]
	global_store_dwordx4 v[210:211], v[172:175], off offset:576
	s_lshr_b32 s38, s7, 2
	v_mov_b32_e32 v177, s38
	v_readlane_b32 s38, v250, 41
	v_readlane_b32 s39, v250, 42
	s_add_u32 s38, s38, 0x20fe0000
	s_addc_u32 s39, s39, 0
	v_mov_b32_e32 v176, 0
	s_nop 3
	global_store_dword v176, v177, s[38:39]
	s_cbranch_execz .LBB0_2889

.LBB0_2889:
	v_mov_b32_e32 v133, v132
	s_mov_b64 s[38:39], 0x10000
	v_lshl_add_u64 v[210:211], v[150:151], 0, s[38:39]
	s_mov_b64 s[38:39], 0x20000
	v_lshl_add_u64 v[158:159], v[150:151], 0, s[38:39]
	global_load_dwordx4 v[160:163], v[150:151], off
	global_load_dwordx4 v[164:167], v[150:151], off offset:64
	global_load_dwordx4 v[168:171], v[150:151], off offset:512
	global_load_dwordx4 v[172:175], v[150:151], off offset:576
	global_load_dwordx4 v[176:179], v[210:211], off
	global_load_dwordx4 v[180:183], v[210:211], off offset:64
	global_load_dwordx4 v[184:187], v[210:211], off offset:512
	global_load_dwordx4 v[188:191], v[210:211], off offset:576
	global_load_dwordx4 v[192:195], v[158:159], off
	global_load_dwordx4 v[196:199], v[158:159], off offset:64
	global_load_dwordx4 v[200:203], v[158:159], off offset:512
	global_load_dwordx4 v[204:207], v[158:159], off offset:576
	s_waitcnt vmcnt(0)
	v_pk_fma_f32 v[160:161], v[134:135], v[126:127], v[160:161]
	v_pk_fma_f32 v[162:163], v[132:133], v[128:129], v[162:163]
	v_pk_fma_f32 v[164:165], v[134:135], v[122:123], v[164:165]
	v_pk_fma_f32 v[166:167], v[132:133], v[124:125], v[166:167]
	v_pk_fma_f32 v[168:169], v[134:135], v[118:119], v[168:169]
	v_pk_fma_f32 v[170:171], v[132:133], v[120:121], v[170:171]
	v_pk_fma_f32 v[172:173], v[134:135], v[114:115], v[172:173]
	v_pk_fma_f32 v[174:175], v[132:133], v[116:117], v[174:175]
	global_store_dwordx4 v[150:151], v[160:163], off
	global_store_dwordx4 v[150:151], v[164:167], off offset:64
	global_store_dwordx4 v[150:151], v[168:171], off offset:512
	global_store_dwordx4 v[150:151], v[172:175], off offset:576
	v_pk_fma_f32 v[176:177], v[134:135], v[110:111], v[176:177]
	v_pk_fma_f32 v[178:179], v[132:133], v[112:113], v[178:179]
	v_pk_fma_f32 v[180:181], v[134:135], v[106:107], v[180:181]
	v_pk_fma_f32 v[182:183], v[132:133], v[108:109], v[182:183]
	v_pk_fma_f32 v[184:185], v[134:135], v[102:103], v[184:185]
	v_pk_fma_f32 v[186:187], v[132:133], v[104:105], v[186:187]
	v_pk_fma_f32 v[188:189], v[134:135], v[98:99], v[188:189]
	v_pk_fma_f32 v[190:191], v[132:133], v[100:101], v[190:191]
	global_store_dwordx4 v[210:211], v[176:179], off
	global_store_dwordx4 v[210:211], v[180:183], off offset:64
	global_store_dwordx4 v[210:211], v[184:187], off offset:512
	global_store_dwordx4 v[210:211], v[188:191], off offset:576
	v_pk_fma_f32 v[192:193], v[134:135], v[94:95], v[192:193]
	v_pk_fma_f32 v[194:195], v[132:133], v[96:97], v[194:195]
	v_pk_fma_f32 v[196:197], v[134:135], v[90:91], v[196:197]
	v_pk_fma_f32 v[198:199], v[132:133], v[92:93], v[198:199]
	v_pk_fma_f32 v[200:201], v[134:135], v[86:87], v[200:201]
	v_pk_fma_f32 v[202:203], v[132:133], v[88:89], v[202:203]
	v_pk_fma_f32 v[204:205], v[134:135], v[82:83], v[204:205]
	v_pk_fma_f32 v[206:207], v[132:133], v[84:85], v[206:207]
	global_store_dwordx4 v[158:159], v[192:195], off
	global_store_dwordx4 v[158:159], v[196:199], off offset:64
	global_store_dwordx4 v[158:159], v[200:203], off offset:512
	global_store_dwordx4 v[158:159], v[204:207], off offset:576
	s_mov_b64 s[38:39], 0x30000
	v_lshl_add_u64 v[208:209], v[150:151], 0, s[38:39]
	s_mov_b64 s[38:39], 0x80000
	v_lshl_add_u64 v[210:211], v[150:151], 0, s[38:39]
	s_mov_b64 s[38:39], 0x90000
	v_lshl_add_u64 v[158:159], v[150:151], 0, s[38:39]
	global_load_dwordx4 v[160:163], v[208:209], off
	global_load_dwordx4 v[164:167], v[208:209], off offset:64
	global_load_dwordx4 v[168:171], v[208:209], off offset:512
	global_load_dwordx4 v[172:175], v[208:209], off offset:576
	global_load_dwordx4 v[176:179], v[210:211], off
	global_load_dwordx4 v[180:183], v[210:211], off offset:64
	global_load_dwordx4 v[184:187], v[210:211], off offset:512
	global_load_dwordx4 v[188:191], v[210:211], off offset:576
	global_load_dwordx4 v[192:195], v[158:159], off
	global_load_dwordx4 v[196:199], v[158:159], off offset:64
	global_load_dwordx4 v[200:203], v[158:159], off offset:512
	global_load_dwordx4 v[204:207], v[158:159], off offset:576
	s_waitcnt vmcnt(0)
	v_pk_fma_f32 v[160:161], v[134:135], v[76:77], v[160:161]
	v_pk_fma_f32 v[162:163], v[132:133], v[78:79], v[162:163]
	v_pk_fma_f32 v[164:165], v[134:135], v[72:73], v[164:165]
	v_pk_fma_f32 v[166:167], v[132:133], v[74:75], v[166:167]
	v_pk_fma_f32 v[168:169], v[134:135], v[68:69], v[168:169]
	v_pk_fma_f32 v[170:171], v[132:133], v[70:71], v[170:171]
	v_pk_fma_f32 v[172:173], v[134:135], v[64:65], v[172:173]
	v_pk_fma_f32 v[174:175], v[132:133], v[66:67], v[174:175]
	global_store_dwordx4 v[208:209], v[160:163], off
	global_store_dwordx4 v[208:209], v[164:167], off offset:64
	global_store_dwordx4 v[208:209], v[168:171], off offset:512
	global_store_dwordx4 v[208:209], v[172:175], off offset:576
	v_pk_fma_f32 v[176:177], v[134:135], v[60:61], v[176:177]
	v_pk_fma_f32 v[178:179], v[132:133], v[62:63], v[178:179]
	v_pk_fma_f32 v[180:181], v[134:135], v[56:57], v[180:181]
	v_pk_fma_f32 v[182:183], v[132:133], v[58:59], v[182:183]
	v_pk_fma_f32 v[184:185], v[134:135], v[52:53], v[184:185]
	v_pk_fma_f32 v[186:187], v[132:133], v[54:55], v[186:187]
	v_pk_fma_f32 v[188:189], v[134:135], v[48:49], v[188:189]
	v_pk_fma_f32 v[190:191], v[132:133], v[50:51], v[190:191]
	global_store_dwordx4 v[210:211], v[176:179], off
	global_store_dwordx4 v[210:211], v[180:183], off offset:64
	global_store_dwordx4 v[210:211], v[184:187], off offset:512
	global_store_dwordx4 v[210:211], v[188:191], off offset:576
	v_pk_fma_f32 v[192:193], v[134:135], v[44:45], v[192:193]
	v_pk_fma_f32 v[194:195], v[132:133], v[46:47], v[194:195]
	v_pk_fma_f32 v[196:197], v[134:135], v[40:41], v[196:197]
	v_pk_fma_f32 v[198:199], v[132:133], v[42:43], v[198:199]
	v_pk_fma_f32 v[200:201], v[134:135], v[36:37], v[200:201]
	v_pk_fma_f32 v[202:203], v[132:133], v[38:39], v[202:203]
	v_pk_fma_f32 v[204:205], v[134:135], v[32:33], v[204:205]
	v_pk_fma_f32 v[206:207], v[132:133], v[34:35], v[206:207]
	global_store_dwordx4 v[158:159], v[192:195], off
	global_store_dwordx4 v[158:159], v[196:199], off offset:64
	global_store_dwordx4 v[158:159], v[200:203], off offset:512
	global_store_dwordx4 v[158:159], v[204:207], off offset:576
	s_mov_b64 s[38:39], 0xa0000
	v_lshl_add_u64 v[208:209], v[150:151], 0, s[38:39]
	s_mov_b64 s[38:39], 0xb0000
	v_lshl_add_u64 v[210:211], v[150:151], 0, s[38:39]
	global_load_dwordx4 v[160:163], v[208:209], off
	global_load_dwordx4 v[164:167], v[208:209], off offset:64
	global_load_dwordx4 v[168:171], v[208:209], off offset:512
	global_load_dwordx4 v[172:175], v[208:209], off offset:576
	global_load_dwordx4 v[176:179], v[210:211], off
	global_load_dwordx4 v[180:183], v[210:211], off offset:64
	global_load_dwordx4 v[184:187], v[210:211], off offset:512
	global_load_dwordx4 v[188:191], v[210:211], off offset:576
	s_waitcnt vmcnt(0)
	v_pk_fma_f32 v[160:161], v[134:135], v[28:29], v[160:161]
	v_pk_fma_f32 v[162:163], v[132:133], v[30:31], v[162:163]
	v_pk_fma_f32 v[164:165], v[134:135], v[24:25], v[164:165]
	v_pk_fma_f32 v[166:167], v[132:133], v[26:27], v[166:167]
	v_pk_fma_f32 v[168:169], v[134:135], v[20:21], v[168:169]
	v_pk_fma_f32 v[170:171], v[132:133], v[22:23], v[170:171]
	v_pk_fma_f32 v[172:173], v[134:135], v[16:17], v[172:173]
	v_pk_fma_f32 v[174:175], v[132:133], v[18:19], v[174:175]
	global_store_dwordx4 v[208:209], v[160:163], off
	global_store_dwordx4 v[208:209], v[164:167], off offset:64
	global_store_dwordx4 v[208:209], v[168:171], off offset:512
	global_store_dwordx4 v[208:209], v[172:175], off offset:576
	v_pk_fma_f32 v[176:177], v[134:135], v[12:13], v[176:177]
	v_pk_fma_f32 v[178:179], v[132:133], v[14:15], v[178:179]
	v_pk_fma_f32 v[180:181], v[134:135], v[8:9], v[180:181]
	v_pk_fma_f32 v[182:183], v[132:133], v[10:11], v[182:183]
	v_pk_fma_f32 v[184:185], v[134:135], v[4:5], v[184:185]
	v_pk_fma_f32 v[186:187], v[132:133], v[6:7], v[186:187]
	v_pk_fma_f32 v[188:189], v[134:135], v[0:1], v[188:189]
	v_pk_fma_f32 v[190:191], v[132:133], v[2:3], v[190:191]
	global_store_dwordx4 v[210:211], v[176:179], off
	global_store_dwordx4 v[210:211], v[180:183], off offset:64
	global_store_dwordx4 v[210:211], v[184:187], off offset:512
	global_store_dwordx4 v[210:211], v[188:191], off offset:576
	s_and_b64 vcc, exec, s[42:43]
	s_mov_b64 s[38:39], -1
	s_cbranch_vccnz .LBB0_2866

.LBB0_3018:
	v_readlane_b32 s12, v252, 30
	v_readlane_b32 s13, v252, 31
	v_mov_b32_e32 v0, v226
	s_andn2_b64 vcc, exec, s[12:13]
	s_mov_b32 s26, 0xb606000
	s_cbranch_vccnz .LBB0_3017
	v_readlane_b32 s14, v250, 6
	s_cmp_gt_u32 s14, 0xff
	s_cbranch_scc1 .Lslab_skip_a
	v_and_b32_e32 v2, 63, v226
	v_lshlrev_b32_e32 v2, 4, v2
	v_lshl_add_u32 v2, s14, 12, v2
	v_mov_b32_e32 v3, 0
	v_readlane_b32 s14, v250, 15
	v_readlane_b32 s18, v250, 16
	s_add_u32 s12, s14, 0xb506000
	s_addc_u32 s13, s18, 0
	v_lshl_add_u64 v[4:5], s[12:13], 0, v[2:3]
	global_load_dwordx4 v[8:11], v[4:5], off sc1
	global_load_dwordx4 v[12:15], v[4:5], off offset:1024 sc1
	global_load_dwordx4 v[16:19], v[4:5], off offset:2048 sc1
	global_load_dwordx4 v[20:23], v[4:5], off offset:3072 sc1
	s_add_u32 s12, s14, 0x284e6000
	s_addc_u32 s13, s18, 0
	global_load_dword v6, v3, s[12:13] sc1
	s_add_u32 s12, s14, 0x274e6000
	s_addc_u32 s13, s18, 0
	v_lshl_add_u64 v[24:25], s[12:13], 0, v[2:3]
	s_mov_b64 s[12:13], 0x100000
	v_lshl_add_u64 v[26:27], v[24:25], 0, s[12:13]
	s_mov_b64 s[12:13], 0x200000
	s_waitcnt vmcnt(0)
	v_readfirstlane_b32 s18, v6
	s_lshr_b32 s18, s18, 1
.Lslab_loop_a:
	global_load_dwordx4 v[28:31], v[24:25], off
	global_load_dwordx4 v[32:35], v[24:25], off offset:1024
	global_load_dwordx4 v[36:39], v[24:25], off offset:2048
	global_load_dwordx4 v[40:43], v[24:25], off offset:3072
	global_load_dwordx4 v[44:47], v[26:27], off
	global_load_dwordx4 v[48:51], v[26:27], off offset:1024
	global_load_dwordx4 v[52:55], v[26:27], off offset:2048
	global_load_dwordx4 v[56:59], v[26:27], off offset:3072
	v_lshl_add_u64 v[24:25], v[24:25], 0, s[12:13]
	v_lshl_add_u64 v[26:27], v[26:27], 0, s[12:13]
	s_waitcnt vmcnt(0)
	v_pk_add_f32 v[8:9], v[8:9], v[28:29]
	v_pk_add_f32 v[10:11], v[10:11], v[30:31]
	v_pk_add_f32 v[12:13], v[12:13], v[32:33]
	v_pk_add_f32 v[14:15], v[14:15], v[34:35]
	v_pk_add_f32 v[16:17], v[16:17], v[36:37]
	v_pk_add_f32 v[18:19], v[18:19], v[38:39]
	v_pk_add_f32 v[20:21], v[20:21], v[40:41]
	v_pk_add_f32 v[22:23], v[22:23], v[42:43]
	v_pk_add_f32 v[8:9], v[8:9], v[44:45]
	v_pk_add_f32 v[10:11], v[10:11], v[46:47]
	v_pk_add_f32 v[12:13], v[12:13], v[48:49]
	v_pk_add_f32 v[14:15], v[14:15], v[50:51]
	v_pk_add_f32 v[16:17], v[16:17], v[52:53]
	v_pk_add_f32 v[18:19], v[18:19], v[54:55]
	v_pk_add_f32 v[20:21], v[20:21], v[56:57]
	v_pk_add_f32 v[22:23], v[22:23], v[58:59]
	s_add_i32 s18, s18, -1
	s_cmp_lg_u32 s18, 0
	s_cbranch_scc1 .Lslab_loop_a
	global_store_dwordx4 v[4:5], v[8:11], off
	global_store_dwordx4 v[4:5], v[12:15], off offset:1024
	global_store_dwordx4 v[4:5], v[16:19], off offset:2048
	global_store_dwordx4 v[4:5], v[20:23], off offset:3072
	s_waitcnt vmcnt(0)
.Lslab_skip_a:
	v_and_b32_e32 v1, 64, v235
	v_add_u32_e32 v1, 64, v1
	v_xor_b32_e32 v2, 1, v235
	v_cmp_lt_i32_e32 vcc, v2, v1
	v_and_b32_e32 v0, 63, v0
	v_readlane_b32 s12, v250, 41
	v_cndmask_b32_e32 v2, v235, v2, vcc
	s_waitcnt vmcnt(2)
	v_lshlrev_b32_e32 v60, 2, v2
	v_xor_b32_e32 v2, 2, v235
	v_cmp_lt_i32_e32 vcc, v2, v1
	v_lshlrev_b32_e32 v80, 4, v0
	v_readlane_b32 s13, v250, 42
	v_cndmask_b32_e32 v2, v235, v2, vcc
	v_lshlrev_b32_e32 v61, 2, v2
	v_xor_b32_e32 v2, 4, v235
	v_cmp_lt_i32_e32 vcc, v2, v1
	v_lshl_add_u64 v[36:37], s[12:13], 0, v[80:81]
	v_readlane_b32 s12, v254, 15
	v_cndmask_b32_e32 v2, v235, v2, vcc
	s_waitcnt vmcnt(1)
	v_lshlrev_b32_e32 v62, 2, v2
	v_xor_b32_e32 v2, 8, v235
	v_cmp_lt_i32_e32 vcc, v2, v1
	v_lshlrev_b32_e32 v0, 3, v0
	v_readlane_b32 s13, v254, 16
	v_cndmask_b32_e32 v2, v235, v2, vcc
	v_lshlrev_b32_e32 v63, 2, v2
	v_xor_b32_e32 v2, 16, v235
	v_cmp_lt_i32_e32 vcc, v2, v1
	v_lshl_add_u64 v[38:39], s[4:5], 0, v[80:81]
	s_nop 0
	v_cndmask_b32_e32 v2, v235, v2, vcc
	v_lshlrev_b32_e32 v64, 2, v2
	v_xor_b32_e32 v2, 32, v235
	v_cmp_lt_i32_e32 vcc, v2, v1
	s_nop 1
	v_cndmask_b32_e32 v1, v235, v2, vcc
	v_lshlrev_b32_e32 v65, 2, v1
	v_mov_b32_e32 v1, v81
	v_lshl_add_u64 v[40:41], s[12:13], 0, v[0:1]
	v_readlane_b32 s12, v254, 40
	v_readlane_b32 s13, v254, 41
	s_nop 1
	v_lshl_add_u64 v[42:43], s[12:13], 0, v[80:81]
	v_readlane_b32 s12, v254, 27
	v_readlane_b32 s13, v254, 28
	s_nop 1
	v_lshl_add_u64 v[44:45], s[12:13], 0, v[0:1]
	v_readlane_b32 s12, v250, 6
	s_mov_b32 s7, s12
	v_readlane_b32 s13, v250, 7
	s_branch .LBB0_3021

.LBB0_3319:
	v_lshl_add_u32 v140, s54, 8, v154
	v_ashrrev_i32_e32 v141, 31, v140
	v_readlane_b32 s38, v250, 41
	v_lshl_or_b32 v142, s56, 8, v156
	v_lshlrev_b64 v[144:145], 12, v[140:141]
	v_readlane_b32 s39, v250, 42
	v_ashrrev_i32_e32 v143, 31, v142
	v_or_b32_e32 v148, 16, v140
	v_lshl_add_u64 v[152:153], s[38:39], 0, v[144:145]
	v_or_b32_e32 v146, 32, v140
	v_or_b32_e32 v144, 48, v140
	v_lshl_add_u64 v[150:151], v[142:143], 2, v[152:153]
	s_mov_b64 s[38:39], -1
	s_andn2_b64 vcc, exec, s[58:59]
	v_lshlrev_b64 v[142:143], 2, v[142:143]
	v_ashrrev_i32_e32 v149, 31, v148
	v_ashrrev_i32_e32 v147, 31, v146
	v_ashrrev_i32_e32 v145, 31, v144
	s_cbranch_vccnz .LBB0_3322
	v_readlane_b32 s38, v254, 55
	s_cmp_eq_u32 s38, 0
	s_cbranch_scc1 .Lslab2_atomic
	v_mov_b32_e32 v133, v132
	s_add_i32 s38, s70, -1
	s_mul_i32 s38, s38, s96
	s_add_i32 s38, s38, s2
	s_addk_i32 s38, 0xff00
	s_lshr_b32 s38, s38, 2
	s_lshl_b32 s38, s38, 20
	s_add_u32 s38, s38, 0x1bfe0000
	s_mov_b32 s39, 0
	v_lshl_add_u64 v[208:209], v[150:151], 0, s[38:39]
	v_pk_mul_f32 v[160:161], v[134:135], v[126:127]
	v_pk_mul_f32 v[162:163], v[132:133], v[128:129]
	global_store_dwordx4 v[208:209], v[160:163], off
	v_pk_mul_f32 v[164:165], v[134:135], v[122:123]
	v_pk_mul_f32 v[166:167], v[132:133], v[124:125]
	global_store_dwordx4 v[208:209], v[164:167], off offset:64
	v_pk_mul_f32 v[168:169], v[134:135], v[118:119]
	v_pk_mul_f32 v[170:171], v[132:133], v[120:121]
	global_store_dwordx4 v[208:209], v[168:171], off offset:512
	v_pk_mul_f32 v[172:173], v[134:135], v[114:115]
	v_pk_mul_f32 v[174:175], v[132:133], v[116:117]
	global_store_dwordx4 v[208:209], v[172:175], off offset:576
	s_mov_b64 s[38:39], 0x10000
	v_lshl_add_u64 v[210:211], v[208:209], 0, s[38:39]
	v_pk_mul_f32 v[160:161], v[134:135], v[110:111]
	v_pk_mul_f32 v[162:163], v[132:133], v[112:113]
	global_store_dwordx4 v[210:211], v[160:163], off
	v_pk_mul_f32 v[164:165], v[134:135], v[106:107]
	v_pk_mul_f32 v[166:167], v[132:133], v[108:109]
	global_store_dwordx4 v[210:211], v[164:167], off offset:64
	v_pk_mul_f32 v[168:169], v[134:135], v[102:103]
	v_pk_mul_f32 v[170:171], v[132:133], v[104:105]
	global_store_dwordx4 v[210:211], v[168:171], off offset:512
	v_pk_mul_f32 v[172:173], v[134:135], v[98:99]
	v_pk_mul_f32 v[174:175], v[132:133], v[100:101]
	global_store_dwordx4 v[210:211], v[172:175], off offset:576
	s_mov_b64 s[38:39], 0x20000
	v_lshl_add_u64 v[178:179], v[208:209], 0, s[38:39]
	v_pk_mul_f32 v[160:161], v[134:135], v[94:95]
	v_pk_mul_f32 v[162:163], v[132:133], v[96:97]
	global_store_dwordx4 v[178:179], v[160:163], off
	v_pk_mul_f32 v[164:165], v[134:135], v[90:91]
	v_pk_mul_f32 v[166:167], v[132:133], v[92:93]
	global_store_dwordx4 v[178:179], v[164:167], off offset:64
	v_pk_mul_f32 v[168:169], v[134:135], v[86:87]
	v_pk_mul_f32 v[170:171], v[132:133], v[88:89]
	global_store_dwordx4 v[178:179], v[168:171], off offset:512
	v_pk_mul_f32 v[172:173], v[134:135], v[82:83]
	v_pk_mul_f32 v[174:175], v[132:133], v[84:85]
	global_store_dwordx4 v[178:179], v[172:175], off offset:576
	s_mov_b64 s[38:39], 0x30000
	v_lshl_add_u64 v[210:211], v[208:209], 0, s[38:39]
	v_pk_mul_f32 v[160:161], v[134:135], v[76:77]
	v_pk_mul_f32 v[162:163], v[132:133], v[78:79]
	global_store_dwordx4 v[210:211], v[160:163], off
	v_pk_mul_f32 v[164:165], v[134:135], v[72:73]
	v_pk_mul_f32 v[166:167], v[132:133], v[74:75]
	global_store_dwordx4 v[210:211], v[164:167], off offset:64
	v_pk_mul_f32 v[168:169], v[134:135], v[68:69]
	v_pk_mul_f32 v[170:171], v[132:133], v[70:71]
	global_store_dwordx4 v[210:211], v[168:171], off offset:512
	v_pk_mul_f32 v[172:173], v[134:135], v[64:65]
	v_pk_mul_f32 v[174:175], v[132:133], v[66:67]
	global_store_dwordx4 v[210:211], v[172:175], off offset:576
	s_mov_b64 s[38:39], 0x80000
	v_lshl_add_u64 v[178:179], v[208:209], 0, s[38:39]
	v_pk_mul_f32 v[160:161], v[134:135], v[60:61]
	v_pk_mul_f32 v[162:163], v[132:133], v[62:63]
	global_store_dwordx4 v[178:179], v[160:163], off
	v_pk_mul_f32 v[164:165], v[134:135], v[56:57]
	v_pk_mul_f32 v[166:167], v[132:133], v[58:59]
	global_store_dwordx4 v[178:179], v[164:167], off offset:64
	v_pk_mul_f32 v[168:169], v[134:135], v[52:53]
	v_pk_mul_f32 v[170:171], v[132:133], v[54:55]
	global_store_dwordx4 v[178:179], v[168:171], off offset:512
	v_pk_mul_f32 v[172:173], v[134:135], v[48:49]
	v_pk_mul_f32 v[174:175], v[132:133], v[50:51]
	global_store_dwordx4 v[178:179], v[172:175], off offset:576
	s_mov_b64 s[38:39], 0x90000
	v_lshl_add_u64 v[210:211], v[208:209], 0, s[38:39]
	v_pk_mul_f32 v[160:161], v[134:135], v[44:45]
	v_pk_mul_f32 v[162:163], v[132:133], v[46:47]
	global_store_dwordx4 v[210:211], v[160:163], off
	v_pk_mul_f32 v[164:165], v[134:135], v[40:41]
	v_pk_mul_f32 v[166:167], v[132:133], v[42:43]
	global_store_dwordx4 v[210:211], v[164:167], off offset:64
	v_pk_mul_f32 v[168:169], v[134:135], v[36:37]
	v_pk_mul_f32 v[170:171], v[132:133], v[38:39]
	global_store_dwordx4 v[210:211], v[168:171], off offset:512
	v_pk_mul_f32 v[172:173], v[134:135], v[32:33]
	v_pk_mul_f32 v[174:175], v[132:133], v[34:35]
	global_store_dwordx4 v[210:211], v[172:175], off offset:576
	s_mov_b64 s[38:39], 0xa0000
	v_lshl_add_u64 v[178:179], v[208:209], 0, s[38:39]
	v_pk_mul_f32 v[160:161], v[134:135], v[28:29]
	v_pk_mul_f32 v[162:163], v[132:133], v[30:31]
	global_store_dwordx4 v[178:179], v[160:163], off
	v_pk_mul_f32 v[164:165], v[134:135], v[24:25]
	v_pk_mul_f32 v[166:167], v[132:133], v[26:27]
	global_store_dwordx4 v[178:179], v[164:167], off offset:64
	v_pk_mul_f32 v[168:169], v[134:135], v[20:21]
	v_pk_mul_f32 v[170:171], v[132:133], v[22:23]
	global_store_dwordx4 v[178:179], v[168:171], off offset:512
	v_pk_mul_f32 v[172:173], v[134:135], v[16:17]
	v_pk_mul_f32 v[174:175], v[132:133], v[18:19]
	global_store_dwordx4 v[178:179], v[172:175], off offset:576
	s_mov_b64 s[38:39], 0xb0000
	v_lshl_add_u64 v[210:211], v[208:209], 0, s[38:39]
	v_pk_mul_f32 v[160:161], v[134:135], v[12:13]
	v_pk_mul_f32 v[162:163], v[132:133], v[14:15]
	global_store_dwordx4 v[210:211], v[160:163], off
	v_pk_mul_f32 v[164:165], v[134:135], v[8:9]
	v_pk_mul_f32 v[166:167], v[132:133], v[10:11]
	global_store_dwordx4 v[210:211], v[164:167], off offset:64
	v_pk_mul_f32 v[168:169], v[134:135], v[4:5]
	v_pk_mul_f32 v[170:171], v[132:133], v[6:7]
	global_store_dwordx4 v[210:211], v[168:171], off offset:512
	v_pk_mul_f32 v[172:173], v[134:135], v[0:1]
	v_pk_mul_f32 v[174:175], v[132:133], v[2:3]
	global_store_dwordx4 v[210:211], v[172:175], off offset:576
	v_mov_b32_e32 v177, 16
	v_readlane_b32 s38, v250, 41
	v_readlane_b32 s39, v250, 42
	s_add_u32 s38, s38, 0x20fe0000
	s_addc_u32 s39, s39, 0
	v_mov_b32_e32 v176, 0
	s_nop 3
	global_store_dword v176, v177, s[38:39]
	s_branch .Lslab2_done
.Lslab2_atomic:
	v_mul_f32_e32 v133, v132, v126
	global_atomic_add_f32 v[150:151], v133, off
	v_mul_f32_e32 v133, v132, v127
	global_atomic_add_f32 v[150:151], v133, off offset:4
	v_mul_f32_e32 v133, v132, v128
	global_atomic_add_f32 v[150:151], v133, off offset:8
	v_mul_f32_e32 v133, v132, v129
	global_atomic_add_f32 v[150:151], v133, off offset:12
	v_mul_f32_e32 v133, v132, v122
	global_atomic_add_f32 v[150:151], v133, off offset:64
	v_mul_f32_e32 v133, v132, v123
	global_atomic_add_f32 v[150:151], v133, off offset:68
	v_mul_f32_e32 v133, v132, v124
	global_atomic_add_f32 v[150:151], v133, off offset:72
	v_mul_f32_e32 v133, v132, v125
	global_atomic_add_f32 v[150:151], v133, off offset:76
	v_mul_f32_e32 v133, v132, v118
	global_atomic_add_f32 v[150:151], v133, off offset:512
	v_mul_f32_e32 v133, v132, v119
	global_atomic_add_f32 v[150:151], v133, off offset:516
	v_mul_f32_e32 v133, v132, v120
	global_atomic_add_f32 v[150:151], v133, off offset:520
	v_mul_f32_e32 v133, v132, v121
	global_atomic_add_f32 v[150:151], v133, off offset:524
	v_mul_f32_e32 v133, v132, v114
	global_atomic_add_f32 v[150:151], v133, off offset:576
	v_mul_f32_e32 v133, v132, v115
	v_readlane_b32 s38, v250, 41
	global_atomic_add_f32 v[150:151], v133, off offset:580
	v_mul_f32_e32 v133, v132, v116
	v_lshlrev_b64 v[158:159], 12, v[148:149]
	v_readlane_b32 s39, v250, 42
	global_atomic_add_f32 v[150:151], v133, off offset:584
	v_mul_f32_e32 v133, v132, v117
	v_lshl_add_u64 v[158:159], s[38:39], 0, v[158:159]
	global_atomic_add_f32 v[150:151], v133, off offset:588
	v_lshl_add_u64 v[158:159], v[158:159], 0, v[142:143]
	v_mul_f32_e32 v133, v132, v110
	global_atomic_add_f32 v[158:159], v133, off
	v_mul_f32_e32 v133, v132, v111
	global_atomic_add_f32 v[158:159], v133, off offset:4
	v_mul_f32_e32 v133, v132, v112
	global_atomic_add_f32 v[158:159], v133, off offset:8
	v_mul_f32_e32 v133, v132, v113
	global_atomic_add_f32 v[158:159], v133, off offset:12
	v_mul_f32_e32 v133, v132, v106
	global_atomic_add_f32 v[158:159], v133, off offset:64
	v_mul_f32_e32 v133, v132, v107
	global_atomic_add_f32 v[158:159], v133, off offset:68
	v_mul_f32_e32 v133, v132, v108
	global_atomic_add_f32 v[158:159], v133, off offset:72
	v_mul_f32_e32 v133, v132, v109
	global_atomic_add_f32 v[158:159], v133, off offset:76
	v_mul_f32_e32 v133, v132, v102
	global_atomic_add_f32 v[158:159], v133, off offset:512
	v_mul_f32_e32 v133, v132, v103
	global_atomic_add_f32 v[158:159], v133, off offset:516
	v_mul_f32_e32 v133, v132, v104
	global_atomic_add_f32 v[158:159], v133, off offset:520
	v_mul_f32_e32 v133, v132, v105
	global_atomic_add_f32 v[158:159], v133, off offset:524
	v_mul_f32_e32 v133, v132, v98
	global_atomic_add_f32 v[158:159], v133, off offset:576
	v_mul_f32_e32 v133, v132, v99
	global_atomic_add_f32 v[158:159], v133, off offset:580
	v_mul_f32_e32 v133, v132, v100
	global_atomic_add_f32 v[158:159], v133, off offset:584
	v_mul_f32_e32 v133, v132, v101
	global_atomic_add_f32 v[158:159], v133, off offset:588
	v_lshlrev_b64 v[158:159], 12, v[146:147]
	v_lshl_add_u64 v[158:159], s[38:39], 0, v[158:159]
	v_lshl_add_u64 v[158:159], v[158:159], 0, v[142:143]
	v_mul_f32_e32 v133, v132, v94
	global_atomic_add_f32 v[158:159], v133, off
	v_mul_f32_e32 v133, v132, v95
	global_atomic_add_f32 v[158:159], v133, off offset:4
	v_mul_f32_e32 v133, v132, v96
	global_atomic_add_f32 v[158:159], v133, off offset:8
	v_mul_f32_e32 v133, v132, v97
	global_atomic_add_f32 v[158:159], v133, off offset:12
	v_mul_f32_e32 v133, v132, v90
	global_atomic_add_f32 v[158:159], v133, off offset:64
	v_mul_f32_e32 v133, v132, v91
	global_atomic_add_f32 v[158:159], v133, off offset:68
	v_mul_f32_e32 v133, v132, v92
	global_atomic_add_f32 v[158:159], v133, off offset:72
	v_mul_f32_e32 v133, v132, v93
	global_atomic_add_f32 v[158:159], v133, off offset:76
	v_mul_f32_e32 v133, v132, v86
	global_atomic_add_f32 v[158:159], v133, off offset:512
	v_mul_f32_e32 v133, v132, v87
	global_atomic_add_f32 v[158:159], v133, off offset:516
	v_mul_f32_e32 v133, v132, v88
	global_atomic_add_f32 v[158:159], v133, off offset:520
	v_mul_f32_e32 v133, v132, v89
	global_atomic_add_f32 v[158:159], v133, off offset:524
	v_mul_f32_e32 v133, v132, v82
	global_atomic_add_f32 v[158:159], v133, off offset:576
	v_mul_f32_e32 v133, v132, v83
	global_atomic_add_f32 v[158:159], v133, off offset:580
	v_mul_f32_e32 v133, v132, v84
	global_atomic_add_f32 v[158:159], v133, off offset:584
	v_mul_f32_e32 v133, v132, v85
	global_atomic_add_f32 v[158:159], v133, off offset:588
	v_lshlrev_b64 v[158:159], 12, v[144:145]
	v_lshl_add_u64 v[158:159], s[38:39], 0, v[158:159]
	v_lshl_add_u64 v[158:159], v[158:159], 0, v[142:143]
	v_mul_f32_e32 v133, v132, v76
	global_atomic_add_f32 v[158:159], v133, off
	v_mul_f32_e32 v133, v132, v77
	global_atomic_add_f32 v[158:159], v133, off offset:4
	v_mul_f32_e32 v133, v132, v78
	global_atomic_add_f32 v[158:159], v133, off offset:8
	v_mul_f32_e32 v133, v132, v79
	global_atomic_add_f32 v[158:159], v133, off offset:12
	v_mul_f32_e32 v133, v132, v72
	global_atomic_add_f32 v[158:159], v133, off offset:64
	v_mul_f32_e32 v133, v132, v73
	global_atomic_add_f32 v[158:159], v133, off offset:68
	v_mul_f32_e32 v133, v132, v74
	global_atomic_add_f32 v[158:159], v133, off offset:72
	v_mul_f32_e32 v133, v132, v75
	global_atomic_add_f32 v[158:159], v133, off offset:76
	v_mul_f32_e32 v133, v132, v68
	global_atomic_add_f32 v[158:159], v133, off offset:512
	v_mul_f32_e32 v133, v132, v69
	global_atomic_add_f32 v[158:159], v133, off offset:516
	v_mul_f32_e32 v133, v132, v70
	global_atomic_add_f32 v[158:159], v133, off offset:520
	v_mul_f32_e32 v133, v132, v71
	global_atomic_add_f32 v[158:159], v133, off offset:524
	v_mul_f32_e32 v133, v132, v64
	global_atomic_add_f32 v[158:159], v133, off offset:576
	v_mul_f32_e32 v133, v132, v65
	global_atomic_add_f32 v[158:159], v133, off offset:580
	v_mul_f32_e32 v133, v132, v66
	v_lshl_add_u64 v[152:153], v[152:153], 0, v[142:143]
	s_mov_b32 s19, 0x80000
	global_atomic_add_f32 v[158:159], v133, off offset:584
	v_mul_f32_e32 v133, v132, v67
	v_add_co_u32_e32 v160, vcc, s19, v152
	global_atomic_add_f32 v[158:159], v133, off offset:588
	s_mov_b64 s[38:39], 0x80000
	v_mul_f32_e32 v133, v132, v60
	v_addc_co_u32_e32 v161, vcc, 0, v153, vcc
	v_lshl_add_u64 v[158:159], v[152:153], 0, s[38:39]
	global_atomic_add_f32 v[160:161], v133, off
	v_mul_f32_e32 v133, v132, v61
	global_atomic_add_f32 v[158:159], v133, off offset:4
	v_mul_f32_e32 v133, v132, v62
	global_atomic_add_f32 v[158:159], v133, off offset:8
	v_mul_f32_e32 v133, v132, v63
	global_atomic_add_f32 v[158:159], v133, off offset:12
	v_mul_f32_e32 v133, v132, v56
	global_atomic_add_f32 v[158:159], v133, off offset:64
	v_mul_f32_e32 v133, v132, v57
	global_atomic_add_f32 v[158:159], v133, off offset:68
	v_mul_f32_e32 v133, v132, v58
	global_atomic_add_f32 v[158:159], v133, off offset:72
	v_mul_f32_e32 v133, v132, v59
	global_atomic_add_f32 v[158:159], v133, off offset:76
	v_mul_f32_e32 v133, v132, v52
	global_atomic_add_f32 v[158:159], v133, off offset:512
	v_mul_f32_e32 v133, v132, v53
	global_atomic_add_f32 v[158:159], v133, off offset:516
	v_mul_f32_e32 v133, v132, v54
	global_atomic_add_f32 v[158:159], v133, off offset:520
	v_mul_f32_e32 v133, v132, v55
	global_atomic_add_f32 v[158:159], v133, off offset:524
	v_mul_f32_e32 v133, v132, v48
	global_atomic_add_f32 v[158:159], v133, off offset:576
	v_mul_f32_e32 v133, v132, v49
	global_atomic_add_f32 v[158:159], v133, off offset:580
	v_mul_f32_e32 v133, v132, v50
	s_mov_b32 s19, 0x90000
	global_atomic_add_f32 v[158:159], v133, off offset:584
	v_mul_f32_e32 v133, v132, v51
	v_add_co_u32_e32 v160, vcc, s19, v152
	global_atomic_add_f32 v[158:159], v133, off offset:588
	s_mov_b64 s[38:39], 0x90000
	v_mul_f32_e32 v133, v132, v44
	v_addc_co_u32_e32 v161, vcc, 0, v153, vcc
	v_lshl_add_u64 v[158:159], v[152:153], 0, s[38:39]
	global_atomic_add_f32 v[160:161], v133, off
	v_mul_f32_e32 v133, v132, v45
	global_atomic_add_f32 v[158:159], v133, off offset:4
	v_mul_f32_e32 v133, v132, v46
	global_atomic_add_f32 v[158:159], v133, off offset:8
	v_mul_f32_e32 v133, v132, v47
	global_atomic_add_f32 v[158:159], v133, off offset:12
	v_mul_f32_e32 v133, v132, v40
	global_atomic_add_f32 v[158:159], v133, off offset:64
	v_mul_f32_e32 v133, v132, v41
	global_atomic_add_f32 v[158:159], v133, off offset:68
	v_mul_f32_e32 v133, v132, v42
	global_atomic_add_f32 v[158:159], v133, off offset:72
	v_mul_f32_e32 v133, v132, v43
	global_atomic_add_f32 v[158:159], v133, off offset:76
	v_mul_f32_e32 v133, v132, v36
	global_atomic_add_f32 v[158:159], v133, off offset:512
	v_mul_f32_e32 v133, v132, v37
	global_atomic_add_f32 v[158:159], v133, off offset:516
	v_mul_f32_e32 v133, v132, v38
	global_atomic_add_f32 v[158:159], v133, off offset:520
	v_mul_f32_e32 v133, v132, v39
	global_atomic_add_f32 v[158:159], v133, off offset:524
	v_mul_f32_e32 v133, v132, v32
	global_atomic_add_f32 v[158:159], v133, off offset:576
	v_mul_f32_e32 v133, v132, v33
	global_atomic_add_f32 v[158:159], v133, off offset:580
	v_mul_f32_e32 v133, v132, v34
	s_mov_b32 s19, 0xa0000
	global_atomic_add_f32 v[158:159], v133, off offset:584
	v_mul_f32_e32 v133, v132, v35
	v_add_co_u32_e32 v160, vcc, s19, v152
	global_atomic_add_f32 v[158:159], v133, off offset:588
	s_mov_b64 s[38:39], 0xa0000
	v_mul_f32_e32 v133, v132, v28
	v_addc_co_u32_e32 v161, vcc, 0, v153, vcc
	v_lshl_add_u64 v[158:159], v[152:153], 0, s[38:39]
	global_atomic_add_f32 v[160:161], v133, off
	v_mul_f32_e32 v133, v132, v29
	global_atomic_add_f32 v[158:159], v133, off offset:4
	v_mul_f32_e32 v133, v132, v30
	global_atomic_add_f32 v[158:159], v133, off offset:8
	v_mul_f32_e32 v133, v132, v31
	global_atomic_add_f32 v[158:159], v133, off offset:12
	v_mul_f32_e32 v133, v132, v24
	global_atomic_add_f32 v[158:159], v133, off offset:64
	v_mul_f32_e32 v133, v132, v25
	global_atomic_add_f32 v[158:159], v133, off offset:68
	v_mul_f32_e32 v133, v132, v26
	global_atomic_add_f32 v[158:159], v133, off offset:72
	v_mul_f32_e32 v133, v132, v27
	global_atomic_add_f32 v[158:159], v133, off offset:76
	v_mul_f32_e32 v133, v132, v20
	global_atomic_add_f32 v[158:159], v133, off offset:512
	v_mul_f32_e32 v133, v132, v21
	global_atomic_add_f32 v[158:159], v133, off offset:516
	v_mul_f32_e32 v133, v132, v22
	global_atomic_add_f32 v[158:159], v133, off offset:520
	v_mul_f32_e32 v133, v132, v23
	global_atomic_add_f32 v[158:159], v133, off offset:524
	v_mul_f32_e32 v133, v132, v16
	global_atomic_add_f32 v[158:159], v133, off offset:576
	v_mul_f32_e32 v133, v132, v17
	global_atomic_add_f32 v[158:159], v133, off offset:580
	v_mul_f32_e32 v133, v132, v18
	global_atomic_add_f32 v[158:159], v133, off offset:584
	v_mul_f32_e32 v133, v132, v19
	s_mov_b64 s[38:39], 0xb0000
	s_mov_b32 s19, 0xb0000
	global_atomic_add_f32 v[158:159], v133, off offset:588
	v_lshl_add_u64 v[158:159], v[152:153], 0, s[38:39]
	v_add_co_u32_e32 v152, vcc, s19, v152
	v_mul_f32_e32 v133, v132, v12
	s_nop 0
	v_addc_co_u32_e32 v153, vcc, 0, v153, vcc
	global_atomic_add_f32 v[152:153], v133, off
	v_mul_f32_e32 v133, v132, v13
	global_atomic_add_f32 v[158:159], v133, off offset:4
	v_mul_f32_e32 v133, v132, v14
	global_atomic_add_f32 v[158:159], v133, off offset:8
	v_mul_f32_e32 v133, v132, v15
	global_atomic_add_f32 v[158:159], v133, off offset:12
	v_mul_f32_e32 v133, v132, v8
	global_atomic_add_f32 v[158:159], v133, off offset:64
	v_mul_f32_e32 v133, v132, v9
	global_atomic_add_f32 v[158:159], v133, off offset:68
	v_mul_f32_e32 v133, v132, v10
	global_atomic_add_f32 v[158:159], v133, off offset:72
	v_mul_f32_e32 v133, v132, v11
	global_atomic_add_f32 v[158:159], v133, off offset:76
	v_mul_f32_e32 v133, v132, v4
	global_atomic_add_f32 v[158:159], v133, off offset:512
	v_mul_f32_e32 v133, v132, v5
	global_atomic_add_f32 v[158:159], v133, off offset:516
	v_mul_f32_e32 v133, v132, v6
	global_atomic_add_f32 v[158:159], v133, off offset:520
	v_mul_f32_e32 v133, v132, v7
	global_atomic_add_f32 v[158:159], v133, off offset:524
	v_mul_f32_e32 v133, v132, v0
	global_atomic_add_f32 v[158:159], v133, off offset:576
	v_mul_f32_e32 v133, v132, v1
	global_atomic_add_f32 v[158:159], v133, off offset:580
	v_mul_f32_e32 v133, v132, v2
	global_atomic_add_f32 v[158:159], v133, off offset:584
	v_mul_f32_e32 v133, v132, v3
	global_atomic_add_f32 v[158:159], v133, off offset:588
.Lslab2_done:
	s_cbranch_execz .LBB0_3323
.LBB0_3321:
	s_and_b64 vcc, exec, s[44:45]
	s_mov_b64 s[38:39], -1
	s_cbranch_vccnz .LBB0_3300
	s_branch .LBB0_3324

.LBB0_3323:
	v_mov_b32_e32 v133, v132
	s_mov_b32 s19, 0x80000
	s_mov_b32 s19, 0x90000
	s_mov_b32 s19, 0xa0000
	s_mov_b32 s19, 0xb0000
	s_mov_b64 s[38:39], 0x10000
	v_lshl_add_u64 v[210:211], v[150:151], 0, s[38:39]
	s_mov_b64 s[38:39], 0x20000
	v_lshl_add_u64 v[158:159], v[150:151], 0, s[38:39]
	global_load_dwordx4 v[160:163], v[150:151], off
	global_load_dwordx4 v[164:167], v[150:151], off offset:64
	global_load_dwordx4 v[168:171], v[150:151], off offset:512
	global_load_dwordx4 v[172:175], v[150:151], off offset:576
	global_load_dwordx4 v[176:179], v[210:211], off
	global_load_dwordx4 v[180:183], v[210:211], off offset:64
	global_load_dwordx4 v[184:187], v[210:211], off offset:512
	global_load_dwordx4 v[188:191], v[210:211], off offset:576
	global_load_dwordx4 v[192:195], v[158:159], off
	global_load_dwordx4 v[196:199], v[158:159], off offset:64
	global_load_dwordx4 v[200:203], v[158:159], off offset:512
	global_load_dwordx4 v[204:207], v[158:159], off offset:576
	s_waitcnt vmcnt(0)
	v_pk_fma_f32 v[160:161], v[134:135], v[126:127], v[160:161]
	v_pk_fma_f32 v[162:163], v[132:133], v[128:129], v[162:163]
	v_pk_fma_f32 v[164:165], v[134:135], v[122:123], v[164:165]
	v_pk_fma_f32 v[166:167], v[132:133], v[124:125], v[166:167]
	v_pk_fma_f32 v[168:169], v[134:135], v[118:119], v[168:169]
	v_pk_fma_f32 v[170:171], v[132:133], v[120:121], v[170:171]
	v_pk_fma_f32 v[172:173], v[134:135], v[114:115], v[172:173]
	v_pk_fma_f32 v[174:175], v[132:133], v[116:117], v[174:175]
	global_store_dwordx4 v[150:151], v[160:163], off
	global_store_dwordx4 v[150:151], v[164:167], off offset:64
	global_store_dwordx4 v[150:151], v[168:171], off offset:512
	global_store_dwordx4 v[150:151], v[172:175], off offset:576
	v_pk_fma_f32 v[176:177], v[134:135], v[110:111], v[176:177]
	v_pk_fma_f32 v[178:179], v[132:133], v[112:113], v[178:179]
	v_pk_fma_f32 v[180:181], v[134:135], v[106:107], v[180:181]
	v_pk_fma_f32 v[182:183], v[132:133], v[108:109], v[182:183]
	v_pk_fma_f32 v[184:185], v[134:135], v[102:103], v[184:185]
	v_pk_fma_f32 v[186:187], v[132:133], v[104:105], v[186:187]
	v_pk_fma_f32 v[188:189], v[134:135], v[98:99], v[188:189]
	v_pk_fma_f32 v[190:191], v[132:133], v[100:101], v[190:191]
	global_store_dwordx4 v[210:211], v[176:179], off
	global_store_dwordx4 v[210:211], v[180:183], off offset:64
	global_store_dwordx4 v[210:211], v[184:187], off offset:512
	global_store_dwordx4 v[210:211], v[188:191], off offset:576
	v_pk_fma_f32 v[192:193], v[134:135], v[94:95], v[192:193]
	v_pk_fma_f32 v[194:195], v[132:133], v[96:97], v[194:195]
	v_pk_fma_f32 v[196:197], v[134:135], v[90:91], v[196:197]
	v_pk_fma_f32 v[198:199], v[132:133], v[92:93], v[198:199]
	v_pk_fma_f32 v[200:201], v[134:135], v[86:87], v[200:201]
	v_pk_fma_f32 v[202:203], v[132:133], v[88:89], v[202:203]
	v_pk_fma_f32 v[204:205], v[134:135], v[82:83], v[204:205]
	v_pk_fma_f32 v[206:207], v[132:133], v[84:85], v[206:207]
	global_store_dwordx4 v[158:159], v[192:195], off
	global_store_dwordx4 v[158:159], v[196:199], off offset:64
	global_store_dwordx4 v[158:159], v[200:203], off offset:512
	global_store_dwordx4 v[158:159], v[204:207], off offset:576
	s_mov_b64 s[38:39], 0x30000
	v_lshl_add_u64 v[208:209], v[150:151], 0, s[38:39]
	s_mov_b64 s[38:39], 0x80000
	v_lshl_add_u64 v[210:211], v[150:151], 0, s[38:39]
	s_mov_b64 s[38:39], 0x90000
	v_lshl_add_u64 v[158:159], v[150:151], 0, s[38:39]
	global_load_dwordx4 v[160:163], v[208:209], off
	global_load_dwordx4 v[164:167], v[208:209], off offset:64
	global_load_dwordx4 v[168:171], v[208:209], off offset:512
	global_load_dwordx4 v[172:175], v[208:209], off offset:576
	global_load_dwordx4 v[176:179], v[210:211], off
	global_load_dwordx4 v[180:183], v[210:211], off offset:64
	global_load_dwordx4 v[184:187], v[210:211], off offset:512
	global_load_dwordx4 v[188:191], v[210:211], off offset:576
	global_load_dwordx4 v[192:195], v[158:159], off
	global_load_dwordx4 v[196:199], v[158:159], off offset:64
	global_load_dwordx4 v[200:203], v[158:159], off offset:512
	global_load_dwordx4 v[204:207], v[158:159], off offset:576
	s_waitcnt vmcnt(0)
	v_pk_fma_f32 v[160:161], v[134:135], v[76:77], v[160:161]
	v_pk_fma_f32 v[162:163], v[132:133], v[78:79], v[162:163]
	v_pk_fma_f32 v[164:165], v[134:135], v[72:73], v[164:165]
	v_pk_fma_f32 v[166:167], v[132:133], v[74:75], v[166:167]
	v_pk_fma_f32 v[168:169], v[134:135], v[68:69], v[168:169]
	v_pk_fma_f32 v[170:171], v[132:133], v[70:71], v[170:171]
	v_pk_fma_f32 v[172:173], v[134:135], v[64:65], v[172:173]
	v_pk_fma_f32 v[174:175], v[132:133], v[66:67], v[174:175]
	global_store_dwordx4 v[208:209], v[160:163], off
	global_store_dwordx4 v[208:209], v[164:167], off offset:64
	global_store_dwordx4 v[208:209], v[168:171], off offset:512
	global_store_dwordx4 v[208:209], v[172:175], off offset:576
	v_pk_fma_f32 v[176:177], v[134:135], v[60:61], v[176:177]
	v_pk_fma_f32 v[178:179], v[132:133], v[62:63], v[178:179]
	v_pk_fma_f32 v[180:181], v[134:135], v[56:57], v[180:181]
	v_pk_fma_f32 v[182:183], v[132:133], v[58:59], v[182:183]
	v_pk_fma_f32 v[184:185], v[134:135], v[52:53], v[184:185]
	v_pk_fma_f32 v[186:187], v[132:133], v[54:55], v[186:187]
	v_pk_fma_f32 v[188:189], v[134:135], v[48:49], v[188:189]
	v_pk_fma_f32 v[190:191], v[132:133], v[50:51], v[190:191]
	global_store_dwordx4 v[210:211], v[176:179], off
	global_store_dwordx4 v[210:211], v[180:183], off offset:64
	global_store_dwordx4 v[210:211], v[184:187], off offset:512
	global_store_dwordx4 v[210:211], v[188:191], off offset:576
	v_pk_fma_f32 v[192:193], v[134:135], v[44:45], v[192:193]
	v_pk_fma_f32 v[194:195], v[132:133], v[46:47], v[194:195]
	v_pk_fma_f32 v[196:197], v[134:135], v[40:41], v[196:197]
	v_pk_fma_f32 v[198:199], v[132:133], v[42:43], v[198:199]
	v_pk_fma_f32 v[200:201], v[134:135], v[36:37], v[200:201]
	v_pk_fma_f32 v[202:203], v[132:133], v[38:39], v[202:203]
	v_pk_fma_f32 v[204:205], v[134:135], v[32:33], v[204:205]
	v_pk_fma_f32 v[206:207], v[132:133], v[34:35], v[206:207]
	global_store_dwordx4 v[158:159], v[192:195], off
	global_store_dwordx4 v[158:159], v[196:199], off offset:64
	global_store_dwordx4 v[158:159], v[200:203], off offset:512
	global_store_dwordx4 v[158:159], v[204:207], off offset:576
	s_mov_b64 s[38:39], 0xa0000
	v_lshl_add_u64 v[208:209], v[150:151], 0, s[38:39]
	s_mov_b64 s[38:39], 0xb0000
	v_lshl_add_u64 v[210:211], v[150:151], 0, s[38:39]
	global_load_dwordx4 v[160:163], v[208:209], off
	global_load_dwordx4 v[164:167], v[208:209], off offset:64
	global_load_dwordx4 v[168:171], v[208:209], off offset:512
	global_load_dwordx4 v[172:175], v[208:209], off offset:576
	global_load_dwordx4 v[176:179], v[210:211], off
	global_load_dwordx4 v[180:183], v[210:211], off offset:64
	global_load_dwordx4 v[184:187], v[210:211], off offset:512
	global_load_dwordx4 v[188:191], v[210:211], off offset:576
	s_waitcnt vmcnt(0)
	v_pk_fma_f32 v[160:161], v[134:135], v[28:29], v[160:161]
	v_pk_fma_f32 v[162:163], v[132:133], v[30:31], v[162:163]
	v_pk_fma_f32 v[164:165], v[134:135], v[24:25], v[164:165]
	v_pk_fma_f32 v[166:167], v[132:133], v[26:27], v[166:167]
	v_pk_fma_f32 v[168:169], v[134:135], v[20:21], v[168:169]
	v_pk_fma_f32 v[170:171], v[132:133], v[22:23], v[170:171]
	v_pk_fma_f32 v[172:173], v[134:135], v[16:17], v[172:173]
	v_pk_fma_f32 v[174:175], v[132:133], v[18:19], v[174:175]
	global_store_dwordx4 v[208:209], v[160:163], off
	global_store_dwordx4 v[208:209], v[164:167], off offset:64
	global_store_dwordx4 v[208:209], v[168:171], off offset:512
	global_store_dwordx4 v[208:209], v[172:175], off offset:576
	v_pk_fma_f32 v[176:177], v[134:135], v[12:13], v[176:177]
	v_pk_fma_f32 v[178:179], v[132:133], v[14:15], v[178:179]
	v_pk_fma_f32 v[180:181], v[134:135], v[8:9], v[180:181]
	v_pk_fma_f32 v[182:183], v[132:133], v[10:11], v[182:183]
	v_pk_fma_f32 v[184:185], v[134:135], v[4:5], v[184:185]
	v_pk_fma_f32 v[186:187], v[132:133], v[6:7], v[186:187]
	v_pk_fma_f32 v[188:189], v[134:135], v[0:1], v[188:189]
	v_pk_fma_f32 v[190:191], v[132:133], v[2:3], v[190:191]
	global_store_dwordx4 v[210:211], v[176:179], off
	global_store_dwordx4 v[210:211], v[180:183], off offset:64
	global_store_dwordx4 v[210:211], v[184:187], off offset:512
	global_store_dwordx4 v[210:211], v[188:191], off offset:576
	s_and_b64 vcc, exec, s[44:45]
	s_mov_b64 s[38:39], -1
	s_cbranch_vccnz .LBB0_3300

.LBB0_3452:
	v_readlane_b32 s26, v250, 6
	v_readlane_b32 s27, v254, 55
	s_cmp_eq_u32 s27, 0
	s_cbranch_scc1 .Lslab_skip_b
	s_cmp_gt_u32 s26, 0xff
	s_cbranch_scc1 .Lslab_skip_b
	v_and_b32_e32 v2, 63, v226
	v_lshlrev_b32_e32 v2, 4, v2
	v_lshl_add_u32 v2, s26, 12, v2
	v_mov_b32_e32 v3, 0
	v_readlane_b32 s26, v250, 15
	v_readlane_b32 s27, v250, 16
	s_add_u32 s18, s26, 0xb506000
	s_addc_u32 s19, s27, 0
	v_lshl_add_u64 v[4:5], s[18:19], 0, v[2:3]
	global_load_dwordx4 v[8:11], v[4:5], off sc1
	global_load_dwordx4 v[12:15], v[4:5], off offset:1024 sc1
	global_load_dwordx4 v[16:19], v[4:5], off offset:2048 sc1
	global_load_dwordx4 v[20:23], v[4:5], off offset:3072 sc1
	s_add_u32 s18, s26, 0x284e6000
	s_addc_u32 s19, s27, 0
	global_load_dword v6, v3, s[18:19] sc1
	s_add_u32 s18, s26, 0x274e6000
	s_addc_u32 s19, s27, 0
	v_lshl_add_u64 v[24:25], s[18:19], 0, v[2:3]
	s_mov_b64 s[18:19], 0x100000
	v_lshl_add_u64 v[26:27], v[24:25], 0, s[18:19]
	s_mov_b64 s[18:19], 0x200000
	s_waitcnt vmcnt(0)
	v_readfirstlane_b32 s27, v6
	s_lshr_b32 s27, s27, 1
.Lslab_loop_b:
	global_load_dwordx4 v[28:31], v[24:25], off
	global_load_dwordx4 v[32:35], v[24:25], off offset:1024
	global_load_dwordx4 v[36:39], v[24:25], off offset:2048
	global_load_dwordx4 v[40:43], v[24:25], off offset:3072
	global_load_dwordx4 v[44:47], v[26:27], off
	global_load_dwordx4 v[48:51], v[26:27], off offset:1024
	global_load_dwordx4 v[52:55], v[26:27], off offset:2048
	global_load_dwordx4 v[56:59], v[26:27], off offset:3072
	v_lshl_add_u64 v[24:25], v[24:25], 0, s[18:19]
	v_lshl_add_u64 v[26:27], v[26:27], 0, s[18:19]
	s_waitcnt vmcnt(0)
	v_pk_add_f32 v[8:9], v[8:9], v[28:29]
	v_pk_add_f32 v[10:11], v[10:11], v[30:31]
	v_pk_add_f32 v[12:13], v[12:13], v[32:33]
	v_pk_add_f32 v[14:15], v[14:15], v[34:35]
	v_pk_add_f32 v[16:17], v[16:17], v[36:37]
	v_pk_add_f32 v[18:19], v[18:19], v[38:39]
	v_pk_add_f32 v[20:21], v[20:21], v[40:41]
	v_pk_add_f32 v[22:23], v[22:23], v[42:43]
	v_pk_add_f32 v[8:9], v[8:9], v[44:45]
	v_pk_add_f32 v[10:11], v[10:11], v[46:47]
	v_pk_add_f32 v[12:13], v[12:13], v[48:49]
	v_pk_add_f32 v[14:15], v[14:15], v[50:51]
	v_pk_add_f32 v[16:17], v[16:17], v[52:53]
	v_pk_add_f32 v[18:19], v[18:19], v[54:55]
	v_pk_add_f32 v[20:21], v[20:21], v[56:57]
	v_pk_add_f32 v[22:23], v[22:23], v[58:59]
	s_add_i32 s27, s27, -1
	s_cmp_lg_u32 s27, 0
	s_cbranch_scc1 .Lslab_loop_b
	global_store_dwordx4 v[4:5], v[8:11], off
	global_store_dwordx4 v[4:5], v[12:15], off offset:1024
	global_store_dwordx4 v[4:5], v[16:19], off offset:2048
	global_store_dwordx4 v[4:5], v[20:23], off offset:3072
	s_waitcnt vmcnt(0)

.LBB0_4105:
	s_bfe_u32 s27, s38, 0x40001
	s_and_b32 s83, s38, 1
	s_and_b64 s[4:5], exec, s[12:13]
	s_cselect_b32 s80, 0x810, 16
	s_lshl_b32 s4, s14, 8
	s_or_b32 s4, s4, s27
	s_addk_i32 s4, 0xf800
	s_ashr_i32 s5, s4, 31
	v_readlane_b32 s76, v255, 4
	s_lshl_b64 s[38:39], s[4:5], 14
	v_readlane_b32 s78, v255, 6
	v_readlane_b32 s79, v255, 7
	s_add_u32 s4, s78, s38
	s_addc_u32 s5, s79, s39
	s_lshl_b32 s92, s27, 8
	v_lshl_add_u64 v[0:1], v[36:37], 0, s[92:93]
	global_load_dwordx2 v[44:45], v[0:1], off
	v_lshl_add_u64 v[0:1], v[38:39], 0, s[92:93]
	global_load_dwordx2 v[46:47], v[0:1], off
	v_lshl_add_u64 v[0:1], v[40:41], 0, s[92:93]
	v_cmp_gt_i32_e32 vcc, s80, v35
	global_load_dwordx2 v[48:49], v[0:1], off
	v_readlane_b32 s77, v255, 5
	v_cndmask_b32_e32 v0, 0, v35, vcc
	v_add_u32_e32 v0, s26, v0
	v_ashrrev_i32_e32 v1, 31, v0
	v_lshlrev_b64 v[0:1], 12, v[0:1]
	v_lshl_or_b32 v50, s27, 6, v34
	v_readlane_b32 s76, v250, 48
	v_lshl_or_b32 v0, v50, 2, v0
	v_readlane_b32 s77, v250, 49
	v_lshl_add_u64 v[8:9], s[28:29], 0, v[0:1]
	v_lshl_or_b32 v78, s83, 5, v53
	v_lshl_add_u64 v[2:3], s[76:77], 0, v[0:1]
	v_readlane_b32 s76, v250, 27
	v_readlane_b32 s77, v250, 28
	v_lshlrev_b32_e32 v80, 8, v78
	s_lshr_b32 s82, s80, 4
	v_lshl_add_u64 v[4:5], s[76:77], 0, v[0:1]
	v_readlane_b32 s76, v250, 39
	v_readlane_b32 s77, v250, 40
	v_readlane_b32 s84, v250, 52
	v_readlane_b32 s85, v250, 53
	v_lshl_add_u64 v[6:7], s[76:77], 0, v[0:1]
	v_readlane_b32 s76, v250, 37
	global_load_dwordx2 v[56:57], v[2:3], off
	global_load_dwordx2 v[58:59], v[4:5], off
	global_load_dwordx2 v[60:61], v[6:7], off
	global_load_dwordx2 v[62:63], v[8:9], off
	v_readlane_b32 s77, v250, 38
	v_mov_b32_e32 v4, v81
	v_mov_b32_e32 v5, v81
	v_lshl_add_u64 v[0:1], s[76:77], 0, v[0:1]
	global_load_dwordx2 v[66:67], v[0:1], off
	v_lshl_add_u64 v[0:1], s[4:5], 0, v[80:81]
	v_lshlrev_b32_e32 v80, 2, v32
	v_readlane_b32 s4, v250, 54
	v_lshl_add_u64 v[54:55], v[0:1], 0, v[80:81]
	v_or_b32_e32 v0, s83, v51
	s_add_u32 s78, s4, s92
	v_readlane_b32 s4, v250, 55
	v_cmp_eq_u32_e64 s[76:77], 0, v0
	s_addc_u32 s79, s4, 0
	v_lshlrev_b32_e32 v0, 2, v78
	v_mov_b32_e32 v1, v81
	v_lshl_add_u64 v[64:65], s[78:79], 0, v[0:1]
	v_lshl_or_b32 v0, s83, 13, v77
	s_lshl_b32 s4, s27, 2
	v_or_b32_e32 v0, s38, v0
	v_mov_b32_e32 v1, s39
	s_add_u32 s4, s84, s4
	v_lshl_add_u64 v[68:69], v[42:43], 0, v[0:1]
	v_mov_b32_e32 v6, v81
	v_mov_b32_e32 v7, v81
	v_mov_b64_e32 v[0:1], v[4:5]
	v_lshlrev_b32_e32 v52, 6, v78
	s_mov_b32 s81, 0
	s_addc_u32 s5, s85, 0
	v_add_u32_e32 v79, s26, v33
	s_waitcnt vmcnt(40)
	v_lshl_add_u32 v82, s83, 7, v76
	v_mov_b64_e32 v[2:3], v[6:7]
	s_and_b64 vcc, exec, s[42:43]
	s_cbranch_vccnz .Lwkv_setup_done
	v_bfe_u32 v105, v226, 4, 4
	v_and_b32_e32 v104, 15, v226
	s_cmp_eq_u32 s83, 0
	s_cselect_b64 s[38:39], -1, 0
	v_cmp_eq_u32_e64 s[76:77], 0, v104
	v_lshlrev_b32_e32 v104, 4, v104
	s_and_b64 s[76:77], s[76:77], s[38:39]
	s_lshl_b32 s38, s27, 8
	v_lshl_add_u32 v73, v105, 8, v104
	v_add_u32_e32 v104, s38, v104
	v_mov_b32_e32 v4, v104
	v_mov_b32_e32 v5, 0
	v_readlane_b32 s38, v255, 12
	v_readlane_b32 s39, v255, 13
	s_nop 1
	v_lshl_add_u64 v[6:7], s[38:39], 0, v[4:5]
	global_load_dwordx4 v[8:11], v[6:7], off
	v_readlane_b32 s38, v255, 14
	v_readlane_b32 s39, v255, 15
	s_nop 1
	v_lshl_add_u64 v[6:7], s[38:39], 0, v[4:5]
	global_load_dwordx4 v[12:15], v[6:7], off
	v_readlane_b32 s38, v255, 16
	v_readlane_b32 s39, v255, 17
	s_nop 1
	v_lshl_add_u64 v[6:7], s[38:39], 0, v[4:5]
	global_load_dwordx4 v[16:19], v[6:7], off
	v_add_u32_e32 v4, s26, v105
	v_lshlrev_b32_e32 v4, 12, v4
	v_or_b32_e32 v4, v4, v104
	v_mov_b32_e32 v5, 0
	v_readlane_b32 s38, v250, 48
	v_readlane_b32 s39, v250, 49
	s_nop 1
	v_lshl_add_u64 v[6:7], s[38:39], 0, v[4:5]
	global_load_dwordx4 v[84:87], v[6:7], off
	v_readlane_b32 s38, v250, 27
	v_readlane_b32 s39, v250, 28
	s_nop 1
	v_lshl_add_u64 v[6:7], s[38:39], 0, v[4:5]
	global_load_dwordx4 v[88:91], v[6:7], off
	v_readlane_b32 s38, v250, 39
	v_readlane_b32 s39, v250, 40
	s_nop 1
	v_lshl_add_u64 v[6:7], s[38:39], 0, v[4:5]
	global_load_dwordx4 v[92:95], v[6:7], off
	v_lshl_add_u64 v[6:7], s[28:29], 0, v[4:5]
	global_load_dwordx4 v[96:99], v[6:7], off
	v_readlane_b32 s38, v250, 37
	v_readlane_b32 s39, v250, 38
	s_nop 1
	v_lshl_add_u64 v[6:7], s[38:39], 0, v[4:5]
	global_load_dwordx4 v[100:103], v[6:7], off
.Lwkv_setup_done:
	s_barrier
	s_branch .LBB0_4108

.LBB0_4108:
	s_lshl_b32 s83, s81, 4
	s_bitcmp1_b32 s81, 0
	s_cselect_b32 s85, 0x1800, 0
	s_add_i32 s81, s81, 1
	s_lshl_b32 s38, s85, 2
	s_add_i32 s84, s38, 0
	s_and_b64 vcc, exec, s[42:43]
	s_cbranch_vccnz .Lwkv_derive_done
	s_waitcnt vmcnt(0)
	v_pk_mul_f32 v[20:21], v[88:89], v[8:9]
	v_pk_mul_f32 v[22:23], v[90:91], v[10:11]
	v_pk_add_f32 v[24:25], v[100:101], -1.0 op_sel_hi:[1,0]
	v_pk_add_f32 v[26:27], v[102:103], -1.0 op_sel_hi:[1,0]
	v_pk_mul_f32 v[28:29], v[20:21], v[20:21]
	v_pk_fma_f32 v[28:29], v[22:23], v[22:23], v[28:29]
	v_pk_fma_f32 v[24:25], v[12:13], v[24:25], 1.0 op_sel_hi:[1,1,0]
	v_pk_fma_f32 v[26:27], v[14:15], v[26:27], 1.0 op_sel_hi:[1,1,0]
	v_add_f32_e32 v28, v28, v29
	v_pk_mul_f32 v[24:25], v[88:89], v[24:25]
	v_pk_mul_f32 v[26:27], v[90:91], v[26:27]
	v_add_f32_dpp v28, v28, v28 quad_perm:[1,0,3,2] row_mask:0xf bank_mask:0xf bound_ctrl:1
	v_pk_mul_f32 v[4:5], v[84:85], v[24:25]
	v_pk_mul_f32 v[6:7], v[86:87], v[26:27]
	v_add_f32_dpp v28, v28, v28 quad_perm:[2,3,0,1] row_mask:0xf bank_mask:0xf bound_ctrl:1
	v_pk_mul_f32 v[4:5], v[4:5], v[16:17]
	v_pk_fma_f32 v[4:5], v[6:7], v[18:19], v[4:5]
	v_add_f32_dpp v28, v28, v28 row_half_mirror row_mask:0xf bank_mask:0xf bound_ctrl:1
	v_add_f32_e32 v30, v4, v5
	v_pk_mul_f32 v[0:1], v[20:21], v[100:101]
	v_add_f32_dpp v28, v28, v28 row_mirror row_mask:0xf bank_mask:0xf bound_ctrl:1
	v_add_f32_dpp v30, v30, v30 quad_perm:[1,0,3,2] row_mask:0xf bank_mask:0xf bound_ctrl:1
	v_pk_mul_f32 v[2:3], v[22:23], v[102:103]
	v_sqrt_f32_e32 v28, v28
	v_add_f32_dpp v30, v30, v30 quad_perm:[2,3,0,1] row_mask:0xf bank_mask:0xf bound_ctrl:1
	v_max_f32_e32 v28, 0x2b8cbccc, v28
	s_nop 0
	v_add_f32_dpp v30, v30, v30 row_half_mirror row_mask:0xf bank_mask:0xf bound_ctrl:1
	v_rcp_f32_e32 v28, v28
	s_nop 0
	v_add_f32_dpp v30, v30, v30 row_mirror row_mask:0xf bank_mask:0xf bound_ctrl:1
	v_pk_mul_f32 v[20:21], v[20:21], v[28:29] op_sel_hi:[1,0]
	v_pk_mul_f32 v[22:23], v[22:23], v[28:29] op_sel_hi:[1,0]
	v_pk_mul_f32 v[0:1], v[0:1], v[28:29] op_sel_hi:[1,0]
	v_pk_mul_f32 v[2:3], v[2:3], v[28:29] op_sel_hi:[1,0]
	v_add_u32_e32 v4, s83, v105
	v_add_u32_e32 v4, s26, v4
	v_lshlrev_b32_e32 v4, 6, v4
	v_mov_b32_e32 v5, 0
	v_lshl_add_u64 v[4:5], s[4:5], 0, v[4:5]
	s_and_saveexec_b64 s[38:39], s[76:77]
	global_store_dword v[4:5], v30, off
	s_or_b64 exec, exec, s[38:39]
	v_add_u32_e32 v31, s84, v73
	ds_write_b128 v31, v[96:99]
	ds_write_b128 v31, v[20:23] offset:4096
	ds_write_b128 v31, v[0:3] offset:8192
	ds_write_b128 v31, v[24:27] offset:12288
	ds_write_b128 v31, v[84:87] offset:16384
	ds_write_b128 v31, v[92:95] offset:20480
	s_cmp_ge_u32 s81, s82
	s_cbranch_scc1 .Lwkv_derive_done
	v_lshl_add_u32 v4, s81, 4, v105
	v_add_u32_e32 v4, s26, v4
	v_lshlrev_b32_e32 v4, 12, v4
	v_or_b32_e32 v4, v4, v104
	v_mov_b32_e32 v5, 0
	v_readlane_b32 s38, v250, 48
	v_readlane_b32 s39, v250, 49
	s_nop 1
	v_lshl_add_u64 v[6:7], s[38:39], 0, v[4:5]
	global_load_dwordx4 v[84:87], v[6:7], off
	v_readlane_b32 s38, v250, 27
	v_readlane_b32 s39, v250, 28
	s_nop 1
	v_lshl_add_u64 v[6:7], s[38:39], 0, v[4:5]
	global_load_dwordx4 v[88:91], v[6:7], off
	v_readlane_b32 s38, v250, 39
	v_readlane_b32 s39, v250, 40
	s_nop 1
	v_lshl_add_u64 v[6:7], s[38:39], 0, v[4:5]
	global_load_dwordx4 v[92:95], v[6:7], off
	v_lshl_add_u64 v[6:7], s[28:29], 0, v[4:5]
	global_load_dwordx4 v[96:99], v[6:7], off
	v_readlane_b32 s38, v250, 37
	v_readlane_b32 s39, v250, 38
	s_nop 1
	v_lshl_add_u64 v[6:7], s[38:39], 0, v[4:5]
	global_load_dwordx4 v[100:103], v[6:7], off
